# v41: GU last round split between group members k and k+2 (each half skips its MFMA clusters and A-fragment ds_reads)
# baseline (speedup 1.0000x reference)
.LBB0_1642:
	s_add_i32 s29, s29, 1
	s_mul_i32 s2, s29, s48
	s_mul_hi_u32 s3, s29, s49
	s_add_i32 s3, s3, s2
	s_mul_i32 s2, s29, s49
	s_add_u32 s2, s2, s78
	s_addc_u32 s3, s3, s79
	s_mov_b32 s32, 0
	s_cmp_eq_u32 s49, 0x100
	s_cbranch_scc0 .Lgu_nosplit
	s_cmp_eq_u32 s29, 5
	s_cbranch_scc0 .Lgu_not5
	s_and_b32 s2, s78, 0x7f
	s_addk_i32 s2, 0x500
	s_mov_b32 s3, 0
.Lgu_not5:
	s_cmp_eq_u32 s29, 6
	s_cbranch_scc0 .Lgu_nosplit
	s_lshr_b32 s32, s78, 7
	s_add_i32 s32, s32, 1
.Lgu_nosplit:
	v_cmp_gt_i64_e32 vcc, s[2:3], v[140:141]
	v_cmp_lt_i64_e64 s[4:5], s[2:3], v[138:139]
	s_cbranch_vccnz .LBB0_1644
	s_ashr_i32 s3, s2, 31
	s_lshr_b32 s3, s3, 29
	s_add_i32 s3, s2, s3
	s_ashr_i32 s16, s3, 3
	s_and_b32 s3, s3, -8
	s_sub_i32 s2, s2, s3
	s_cmp_lt_i32 s2, 0
	s_cselect_b32 s3, s95, 0xb0
	s_mul_i32 s2, s2, s3
	s_add_i32 s2, s2, s16
	s_mul_hi_i32 s3, s2, 0x2e8ba2e9
	s_lshr_b32 s16, s3, 31
	s_ashr_i32 s3, s3, 5
	s_add_i32 s3, s3, s16
	s_lshl_b32 s16, s3, 3
	s_sub_i32 s17, 64, s16
	s_min_i32 s17, s17, 8
	s_abs_i32 s30, s17
	v_cvt_f32_u32_e32 v2, s30
	s_sub_i32 s35, 0, s30
	s_mulk_i32 s3, 0xb0
	s_sub_i32 s2, s2, s3
	v_rcp_iflag_f32_e32 v2, v2
	s_abs_i32 s3, s2
	s_xor_b32 s31, s2, s17
	s_ashr_i32 s31, s31, 31
	v_mul_f32_e32 v2, 0x4f7ffffe, v2
	v_cvt_u32_f32_e32 v2, v2
	s_nop 0
	v_readfirstlane_b32 s36, v2
	s_mul_i32 s35, s35, s36
	s_mul_hi_u32 s35, s36, s35
	s_add_i32 s36, s36, s35
	s_mul_hi_u32 s35, s3, s36
	s_mul_i32 s36, s35, s30
	s_sub_i32 s3, s3, s36
	s_add_i32 s37, s35, 1
	s_sub_i32 s36, s3, s30
	s_cmp_ge_u32 s3, s30
	s_cselect_b32 s35, s37, s35
	s_cselect_b32 s3, s36, s3
	s_add_i32 s36, s35, 1
	s_cmp_ge_u32 s3, s30
	s_cselect_b32 s3, s36, s35
	s_xor_b32 s3, s3, s31
	s_sub_i32 s30, s3, s31
	s_mul_i32 s3, s30, s17
	s_sub_i32 s2, s2, s3
	s_add_i32 s31, s16, s2

.LBB0_1650:
	s_add_i32 s37, s18, 2
	s_add_u32 s38, s0, 0x80
	s_addc_u32 s19, s1, 0
	s_add_i32 s40, 0, 0x10000
	s_cmp_eq_u32 s28, s18
	s_cselect_b32 s19, s5, s19
	s_cselect_b32 s18, s4, s38
	v_add_u32_e32 v154, s40, v159
	s_cselect_b32 s39, s17, s36
	s_cselect_b32 s38, s16, s35
	s_add_i32 s41, 0, 0x14000
	ds_read_b128 v[164:167], v154
	ds_read_b128 v[168:171], v154 offset:1024
	ds_read_b128 v[174:177], v154 offset:2048
	ds_read_b128 v[178:181], v154 offset:3072
	v_add_u32_e32 v154, s41, v159
	ds_read_b128 v[196:199], v154
	ds_read_b128 v[200:203], v154 offset:1024
	ds_read_b128 v[204:207], v154 offset:2048
	ds_read_b128 v[208:211], v154 offset:3072
	v_lshl_add_u64 v[154:155], s[0:1], 0, v[150:151]
	s_add_i32 m0, s21, 0xc000
	s_cmp_eq_u32 s32, 2
	s_cbranch_scc1 .Lgu_skip_rd1
	ds_read_b128 v[212:215], v163
	ds_read_b128 v[216:219], v163 offset:1024
	ds_read_b128 v[220:223], v163 offset:2048
	ds_read_b128 v[224:227], v163 offset:3072
	ds_read_b128 v[228:231], v163 offset:4096
	ds_read_b128 v[232:235], v163 offset:5120
	ds_read_b128 v[236:239], v163 offset:6144
	ds_read_b128 v[240:243], v163 offset:7168
.Lgu_skip_rd1:
	global_load_lds_dwordx4 v[154:155], off
	v_lshl_add_u64 v[154:155], s[0:1], 0, v[152:153]
	s_add_i32 m0, s21, 0xe000
	s_nop 0
	global_load_lds_dwordx4 v[154:155], off
	s_waitcnt vmcnt(8)
	s_waitcnt lgkmcnt(0)
	s_barrier
	s_cmp_eq_u32 s32, 2
	s_cbranch_scc1 .Lgu_skip_sp1
	s_setprio 1
	s_waitcnt lgkmcnt(0)
	v_mfma_f32_16x16x32_bf16 v[122:125], v[164:167], v[212:215], v[122:125]
	v_mfma_f32_16x16x32_bf16 v[114:117], v[174:177], v[212:215], v[114:117]
	v_mfma_f32_16x16x32_bf16 v[106:109], v[164:167], v[220:223], v[106:109]
	v_mfma_f32_16x16x32_bf16 v[98:101], v[174:177], v[220:223], v[98:101]
	v_mfma_f32_16x16x32_bf16 v[90:93], v[164:167], v[228:231], v[90:93]
	v_mfma_f32_16x16x32_bf16 v[82:85], v[174:177], v[228:231], v[82:85]
	v_mfma_f32_16x16x32_bf16 v[74:77], v[164:167], v[236:239], v[74:77]
	v_mfma_f32_16x16x32_bf16 v[66:69], v[174:177], v[236:239], v[66:69]
	v_mfma_f32_16x16x32_bf16 v[122:125], v[168:171], v[216:219], v[122:125]
	v_mfma_f32_16x16x32_bf16 v[114:117], v[178:181], v[216:219], v[114:117]
	v_mfma_f32_16x16x32_bf16 v[106:109], v[168:171], v[224:227], v[106:109]
	v_mfma_f32_16x16x32_bf16 v[98:101], v[178:181], v[224:227], v[98:101]
	v_mfma_f32_16x16x32_bf16 v[90:93], v[168:171], v[232:235], v[90:93]
	v_mfma_f32_16x16x32_bf16 v[82:85], v[178:181], v[232:235], v[82:85]
	v_mfma_f32_16x16x32_bf16 v[74:77], v[168:171], v[240:243], v[74:77]
	v_mfma_f32_16x16x32_bf16 v[66:69], v[178:181], v[240:243], v[66:69]
	s_setprio 0
	s_setprio 1
	v_mfma_f32_16x16x32_bf16 v[126:129], v[196:199], v[212:215], v[126:129]
	v_mfma_f32_16x16x32_bf16 v[118:121], v[204:207], v[212:215], v[118:121]
	v_mfma_f32_16x16x32_bf16 v[110:113], v[196:199], v[220:223], v[110:113]
	v_mfma_f32_16x16x32_bf16 v[102:105], v[204:207], v[220:223], v[102:105]
	v_mfma_f32_16x16x32_bf16 v[94:97], v[196:199], v[228:231], v[94:97]
	v_mfma_f32_16x16x32_bf16 v[86:89], v[204:207], v[228:231], v[86:89]
	v_mfma_f32_16x16x32_bf16 v[78:81], v[196:199], v[236:239], v[78:81]
	v_mfma_f32_16x16x32_bf16 v[70:73], v[204:207], v[236:239], v[70:73]
	v_mfma_f32_16x16x32_bf16 v[126:129], v[200:203], v[216:219], v[126:129]
	v_mfma_f32_16x16x32_bf16 v[118:121], v[208:211], v[216:219], v[118:121]
	v_mfma_f32_16x16x32_bf16 v[110:113], v[200:203], v[224:227], v[110:113]
	v_mfma_f32_16x16x32_bf16 v[102:105], v[208:211], v[224:227], v[102:105]
	v_mfma_f32_16x16x32_bf16 v[94:97], v[200:203], v[232:235], v[94:97]
	v_mfma_f32_16x16x32_bf16 v[86:89], v[208:211], v[232:235], v[86:89]
	v_mfma_f32_16x16x32_bf16 v[78:81], v[200:203], v[240:243], v[78:81]
	v_mfma_f32_16x16x32_bf16 v[70:73], v[208:211], v[240:243], v[70:73]
	s_setprio 0
.Lgu_skip_sp1:
	s_barrier
	s_add_i32 s40, s40, s20
	v_lshl_add_u64 v[154:155], s[38:39], 0, v[146:147]
	s_mov_b32 m0, s40
	s_cmp_eq_u32 s32, 1
	s_cbranch_scc1 .Lgu_skip_rd2
	ds_read_b128 v[212:215], v163 offset:16384
	ds_read_b128 v[216:219], v163 offset:17408
	ds_read_b128 v[220:223], v163 offset:18432
	ds_read_b128 v[224:227], v163 offset:19456
	ds_read_b128 v[228:231], v163 offset:20480
	ds_read_b128 v[232:235], v163 offset:21504
	ds_read_b128 v[236:239], v163 offset:22528
	ds_read_b128 v[240:243], v163 offset:23552
.Lgu_skip_rd2:
	global_load_lds_dwordx4 v[154:155], off
	s_add_i32 m0, s40, 0x2000
	v_lshl_add_u64 v[182:183], s[38:39], 0, v[142:143]
	s_add_u32 s38, s38, s6
	s_addc_u32 s39, s39, s7
	s_add_i32 s40, s41, s20
	global_load_lds_dwordx4 v[182:183], off
	v_lshl_add_u64 v[244:245], s[38:39], 0, v[146:147]
	s_mov_b32 m0, s40
	v_lshl_add_u64 v[246:247], s[38:39], 0, v[142:143]
	global_load_lds_dwordx4 v[244:245], off
	s_add_i32 m0, s40, 0x2000
	v_lshl_add_u64 v[248:249], s[18:19], 0, v[148:149]
	global_load_lds_dwordx4 v[246:247], off
	s_mov_b32 m0, s21
	v_lshl_add_u64 v[250:251], s[18:19], 0, v[144:145]
	global_load_lds_dwordx4 v[248:249], off
	s_mov_b32 m0, s22
	s_nop 0
	global_load_lds_dwordx4 v[250:251], off
	s_waitcnt vmcnt(8)
	s_waitcnt lgkmcnt(0)
	s_barrier
	s_cmp_eq_u32 s32, 1
	s_cbranch_scc1 .Lgu_skip_sp2
	s_setprio 1
	s_waitcnt lgkmcnt(0)
	v_mfma_f32_16x16x32_bf16 v[58:61], v[164:167], v[212:215], v[58:61]
	v_mfma_f32_16x16x32_bf16 v[50:53], v[174:177], v[212:215], v[50:53]
	v_mfma_f32_16x16x32_bf16 v[42:45], v[164:167], v[220:223], v[42:45]
	v_mfma_f32_16x16x32_bf16 v[34:37], v[174:177], v[220:223], v[34:37]
	v_mfma_f32_16x16x32_bf16 v[26:29], v[164:167], v[228:231], v[26:29]
	v_mfma_f32_16x16x32_bf16 v[18:21], v[174:177], v[228:231], v[18:21]
	v_mfma_f32_16x16x32_bf16 v[10:13], v[164:167], v[236:239], v[10:13]
	v_mfma_f32_16x16x32_bf16 v[6:9], v[174:177], v[236:239], v[6:9]
	v_mfma_f32_16x16x32_bf16 v[58:61], v[168:171], v[216:219], v[58:61]
	v_mfma_f32_16x16x32_bf16 v[50:53], v[178:181], v[216:219], v[50:53]
	v_mfma_f32_16x16x32_bf16 v[42:45], v[168:171], v[224:227], v[42:45]
	v_mfma_f32_16x16x32_bf16 v[34:37], v[178:181], v[224:227], v[34:37]
	v_mfma_f32_16x16x32_bf16 v[26:29], v[168:171], v[232:235], v[26:29]
	v_mfma_f32_16x16x32_bf16 v[18:21], v[178:181], v[232:235], v[18:21]
	v_mfma_f32_16x16x32_bf16 v[10:13], v[168:171], v[240:243], v[10:13]
	v_mfma_f32_16x16x32_bf16 v[6:9], v[178:181], v[240:243], v[6:9]
	s_setprio 0
	s_setprio 1
	v_mfma_f32_16x16x32_bf16 v[62:65], v[196:199], v[212:215], v[62:65]
	v_mfma_f32_16x16x32_bf16 v[54:57], v[204:207], v[212:215], v[54:57]
	v_mfma_f32_16x16x32_bf16 v[46:49], v[196:199], v[220:223], v[46:49]
	v_mfma_f32_16x16x32_bf16 v[38:41], v[204:207], v[220:223], v[38:41]
	v_mfma_f32_16x16x32_bf16 v[30:33], v[196:199], v[228:231], v[30:33]
	v_mfma_f32_16x16x32_bf16 v[22:25], v[204:207], v[228:231], v[22:25]
	v_mfma_f32_16x16x32_bf16 v[14:17], v[196:199], v[236:239], v[14:17]
	v_mfma_f32_16x16x32_bf16 v[2:5], v[204:207], v[236:239], v[2:5]
	v_mfma_f32_16x16x32_bf16 v[62:65], v[200:203], v[216:219], v[62:65]
	v_mfma_f32_16x16x32_bf16 v[54:57], v[208:211], v[216:219], v[54:57]
	v_mfma_f32_16x16x32_bf16 v[46:49], v[200:203], v[224:227], v[46:49]
	v_mfma_f32_16x16x32_bf16 v[38:41], v[208:211], v[224:227], v[38:41]
	v_mfma_f32_16x16x32_bf16 v[30:33], v[200:203], v[232:235], v[30:33]
	v_mfma_f32_16x16x32_bf16 v[22:25], v[208:211], v[232:235], v[22:25]
	v_mfma_f32_16x16x32_bf16 v[14:17], v[200:203], v[240:243], v[14:17]
	v_mfma_f32_16x16x32_bf16 v[2:5], v[208:211], v[240:243], v[2:5]
	s_setprio 0
.Lgu_skip_sp2:
	s_barrier
	s_add_i32 s38, 0, 0x18000
	v_add_u32_e32 v156, s38, v159
	s_add_i32 s39, 0, 0x1c000
	ds_read_b128 v[164:167], v156
	ds_read_b128 v[168:171], v156 offset:1024
	ds_read_b128 v[174:177], v156 offset:2048
	ds_read_b128 v[178:181], v156 offset:3072
	v_add_u32_e32 v156, s39, v159
	ds_read_b128 v[196:199], v156
	ds_read_b128 v[200:203], v156 offset:1024
	ds_read_b128 v[204:207], v156 offset:2048
	ds_read_b128 v[208:211], v156 offset:3072
	s_add_u32 s18, s18, s6
	s_addc_u32 s19, s19, s7
	s_mov_b32 m0, s23
	v_lshl_add_u64 v[252:253], s[18:19], 0, v[148:149]
	s_cmp_eq_u32 s32, 2
	s_cbranch_scc1 .Lgu_skip_rd3
	ds_read_b128 v[212:215], v163 offset:32768
	ds_read_b128 v[216:219], v163 offset:33792
	ds_read_b128 v[220:223], v163 offset:34816
	ds_read_b128 v[224:227], v163 offset:35840
	ds_read_b128 v[228:231], v163 offset:36864
	ds_read_b128 v[232:235], v163 offset:37888
	ds_read_b128 v[236:239], v163 offset:38912
	ds_read_b128 v[240:243], v163 offset:39936
.Lgu_skip_rd3:
	global_load_lds_dwordx4 v[252:253], off
	v_lshl_add_u64 v[252:253], s[18:19], 0, v[144:145]
	s_mov_b32 m0, s24
	s_nop 0
	global_load_lds_dwordx4 v[252:253], off
	s_waitcnt vmcnt(8)
	s_waitcnt lgkmcnt(0)
	s_barrier
	s_cmp_eq_u32 s32, 2
	s_cbranch_scc1 .Lgu_skip_sp3
	s_setprio 1
	s_waitcnt lgkmcnt(0)
	v_mfma_f32_16x16x32_bf16 v[122:125], v[164:167], v[212:215], v[122:125]
	v_mfma_f32_16x16x32_bf16 v[114:117], v[174:177], v[212:215], v[114:117]
	v_mfma_f32_16x16x32_bf16 v[106:109], v[164:167], v[220:223], v[106:109]
	v_mfma_f32_16x16x32_bf16 v[98:101], v[174:177], v[220:223], v[98:101]
	v_mfma_f32_16x16x32_bf16 v[90:93], v[164:167], v[228:231], v[90:93]
	v_mfma_f32_16x16x32_bf16 v[82:85], v[174:177], v[228:231], v[82:85]
	v_mfma_f32_16x16x32_bf16 v[74:77], v[164:167], v[236:239], v[74:77]
	v_mfma_f32_16x16x32_bf16 v[66:69], v[174:177], v[236:239], v[66:69]
	v_mfma_f32_16x16x32_bf16 v[122:125], v[168:171], v[216:219], v[122:125]
	v_mfma_f32_16x16x32_bf16 v[114:117], v[178:181], v[216:219], v[114:117]
	v_mfma_f32_16x16x32_bf16 v[106:109], v[168:171], v[224:227], v[106:109]
	v_mfma_f32_16x16x32_bf16 v[98:101], v[178:181], v[224:227], v[98:101]
	v_mfma_f32_16x16x32_bf16 v[90:93], v[168:171], v[232:235], v[90:93]
	v_mfma_f32_16x16x32_bf16 v[82:85], v[178:181], v[232:235], v[82:85]
	v_mfma_f32_16x16x32_bf16 v[74:77], v[168:171], v[240:243], v[74:77]
	v_mfma_f32_16x16x32_bf16 v[66:69], v[178:181], v[240:243], v[66:69]
	s_setprio 0
	s_setprio 1
	v_mfma_f32_16x16x32_bf16 v[126:129], v[196:199], v[212:215], v[126:129]
	v_mfma_f32_16x16x32_bf16 v[118:121], v[204:207], v[212:215], v[118:121]
	v_mfma_f32_16x16x32_bf16 v[110:113], v[196:199], v[220:223], v[110:113]
	v_mfma_f32_16x16x32_bf16 v[102:105], v[204:207], v[220:223], v[102:105]
	v_mfma_f32_16x16x32_bf16 v[94:97], v[196:199], v[228:231], v[94:97]
	v_mfma_f32_16x16x32_bf16 v[86:89], v[204:207], v[228:231], v[86:89]
	v_mfma_f32_16x16x32_bf16 v[78:81], v[196:199], v[236:239], v[78:81]
	v_mfma_f32_16x16x32_bf16 v[70:73], v[204:207], v[236:239], v[70:73]
	v_mfma_f32_16x16x32_bf16 v[126:129], v[200:203], v[216:219], v[126:129]
	v_mfma_f32_16x16x32_bf16 v[118:121], v[208:211], v[216:219], v[118:121]
	v_mfma_f32_16x16x32_bf16 v[110:113], v[200:203], v[224:227], v[110:113]
	v_mfma_f32_16x16x32_bf16 v[102:105], v[208:211], v[224:227], v[102:105]
	v_mfma_f32_16x16x32_bf16 v[94:97], v[200:203], v[232:235], v[94:97]
	v_mfma_f32_16x16x32_bf16 v[86:89], v[208:211], v[232:235], v[86:89]
	v_mfma_f32_16x16x32_bf16 v[78:81], v[200:203], v[240:243], v[78:81]
	v_mfma_f32_16x16x32_bf16 v[70:73], v[208:211], v[240:243], v[70:73]
	s_setprio 0
.Lgu_skip_sp3:
	s_barrier
	s_add_i32 s18, s38, s20
	v_lshl_add_u64 v[154:155], v[154:155], 0, s[42:43]
	s_mov_b32 m0, s18
	s_cmp_eq_u32 s32, 1
	s_cbranch_scc1 .Lgu_skip_rd4
	ds_read_b128 v[212:215], v163 offset:49152
	ds_read_b128 v[216:219], v163 offset:50176
	ds_read_b128 v[220:223], v163 offset:51200
	ds_read_b128 v[224:227], v163 offset:52224
	ds_read_b128 v[228:231], v163 offset:53248
	ds_read_b128 v[232:235], v163 offset:54272
	ds_read_b128 v[236:239], v163 offset:55296
	ds_read_b128 v[240:243], v163 offset:56320
.Lgu_skip_rd4:
	global_load_lds_dwordx4 v[154:155], off
	v_lshl_add_u64 v[154:155], v[182:183], 0, s[42:43]
	s_add_i32 m0, s18, 0x2000
	s_add_i32 s18, s39, s20
	global_load_lds_dwordx4 v[154:155], off
	v_lshl_add_u64 v[154:155], v[244:245], 0, s[42:43]
	s_mov_b32 m0, s18
	s_nop 0
	global_load_lds_dwordx4 v[154:155], off
	v_lshl_add_u64 v[154:155], v[246:247], 0, s[42:43]
	s_add_i32 m0, s18, 0x2000
	s_nop 0
	global_load_lds_dwordx4 v[154:155], off
	v_lshl_add_u64 v[154:155], v[248:249], 0, s[42:43]
	s_mov_b32 m0, s25
	s_nop 0
	global_load_lds_dwordx4 v[154:155], off
	v_lshl_add_u64 v[154:155], v[250:251], 0, s[42:43]
	s_mov_b32 m0, s26
	s_nop 0
	global_load_lds_dwordx4 v[154:155], off
	s_waitcnt vmcnt(8)
	s_waitcnt lgkmcnt(0)
	s_barrier
	s_cmp_eq_u32 s32, 1
	s_cbranch_scc1 .Lgu_skip_sp4
	s_setprio 1
	s_waitcnt lgkmcnt(0)
	v_mfma_f32_16x16x32_bf16 v[58:61], v[164:167], v[212:215], v[58:61]
	v_mfma_f32_16x16x32_bf16 v[50:53], v[174:177], v[212:215], v[50:53]
	v_mfma_f32_16x16x32_bf16 v[42:45], v[164:167], v[220:223], v[42:45]
	v_mfma_f32_16x16x32_bf16 v[34:37], v[174:177], v[220:223], v[34:37]
	v_mfma_f32_16x16x32_bf16 v[26:29], v[164:167], v[228:231], v[26:29]
	v_mfma_f32_16x16x32_bf16 v[18:21], v[174:177], v[228:231], v[18:21]
	v_mfma_f32_16x16x32_bf16 v[10:13], v[164:167], v[236:239], v[10:13]
	v_mfma_f32_16x16x32_bf16 v[6:9], v[174:177], v[236:239], v[6:9]
	v_mfma_f32_16x16x32_bf16 v[58:61], v[168:171], v[216:219], v[58:61]
	v_mfma_f32_16x16x32_bf16 v[50:53], v[178:181], v[216:219], v[50:53]
	v_mfma_f32_16x16x32_bf16 v[42:45], v[168:171], v[224:227], v[42:45]
	v_mfma_f32_16x16x32_bf16 v[34:37], v[178:181], v[224:227], v[34:37]
	v_mfma_f32_16x16x32_bf16 v[26:29], v[168:171], v[232:235], v[26:29]
	v_mfma_f32_16x16x32_bf16 v[18:21], v[178:181], v[232:235], v[18:21]
	v_mfma_f32_16x16x32_bf16 v[10:13], v[168:171], v[240:243], v[10:13]
	v_mfma_f32_16x16x32_bf16 v[6:9], v[178:181], v[240:243], v[6:9]
	s_setprio 0
	s_setprio 1
	v_mfma_f32_16x16x32_bf16 v[62:65], v[196:199], v[212:215], v[62:65]
	v_mfma_f32_16x16x32_bf16 v[54:57], v[204:207], v[212:215], v[54:57]
	v_mfma_f32_16x16x32_bf16 v[46:49], v[196:199], v[220:223], v[46:49]
	v_mfma_f32_16x16x32_bf16 v[38:41], v[204:207], v[220:223], v[38:41]
	v_mfma_f32_16x16x32_bf16 v[30:33], v[196:199], v[228:231], v[30:33]
	v_mfma_f32_16x16x32_bf16 v[22:25], v[204:207], v[228:231], v[22:25]
	v_mfma_f32_16x16x32_bf16 v[14:17], v[196:199], v[236:239], v[14:17]
	v_mfma_f32_16x16x32_bf16 v[2:5], v[204:207], v[236:239], v[2:5]
	v_mfma_f32_16x16x32_bf16 v[62:65], v[200:203], v[216:219], v[62:65]
	v_mfma_f32_16x16x32_bf16 v[54:57], v[208:211], v[216:219], v[54:57]
	v_mfma_f32_16x16x32_bf16 v[46:49], v[200:203], v[224:227], v[46:49]
	v_mfma_f32_16x16x32_bf16 v[38:41], v[208:211], v[224:227], v[38:41]
	v_mfma_f32_16x16x32_bf16 v[30:33], v[200:203], v[232:235], v[30:33]
	v_mfma_f32_16x16x32_bf16 v[22:25], v[208:211], v[232:235], v[22:25]
	v_mfma_f32_16x16x32_bf16 v[14:17], v[200:203], v[240:243], v[14:17]
	v_mfma_f32_16x16x32_bf16 v[2:5], v[208:211], v[240:243], v[2:5]
	s_setprio 0
.Lgu_skip_sp4:
	s_barrier
	s_add_u32 s0, s0, 0x100
	s_addc_u32 s1, s1, 0
	s_add_u32 s35, s35, 0x100
	s_addc_u32 s36, s36, 0
	s_cmp_ge_i32 s37, s27
	s_mov_b32 s18, s37
	s_cbranch_scc0 .LBB0_1650
.LBB0_1651:
	s_lshl_b32 s0, s34, 8
	v_add_u32_e32 v252, s0, v157
	v_mov_b32_e32 v253, 0
	v_add_u32_e32 v250, 0x80, v252
	v_mov_b32_e32 v251, 0
	v_lshlrev_b64 v[244:245], 6, v[252:253]
	v_lshlrev_b64 v[246:247], 6, v[250:251]
	v_lshl_add_u64 v[244:245], s[72:73], 0, v[244:245]
	v_lshl_add_u64 v[246:247], s[72:73], 0, v[246:247]
	s_cmp_eq_u32 s32, 2
	s_cbranch_scc1 .Lgu_ld_hi
	global_load_dwordx4 v[196:199], v[244:245], off offset:48
	global_load_dwordx4 v[200:203], v[244:245], off offset:32
	global_load_dwordx4 v[204:207], v[244:245], off offset:16
	global_load_dwordx4 v[208:211], v[244:245], off
	global_load_dwordx4 v[212:215], v[244:245], off offset:1072
	global_load_dwordx4 v[216:219], v[244:245], off offset:1056
	global_load_dwordx4 v[220:223], v[244:245], off offset:1040
	global_load_dwordx4 v[224:227], v[244:245], off offset:1024
	global_load_dwordx4 v[228:231], v[244:245], off offset:2096
	global_load_dwordx4 v[232:235], v[244:245], off offset:2080
	global_load_dwordx4 v[236:239], v[244:245], off offset:2064
	global_load_dwordx4 v[240:243], v[244:245], off offset:2048
	global_load_dwordx4 v[164:167], v[244:245], off offset:3120
	global_load_dwordx4 v[168:171], v[244:245], off offset:3104
	global_load_dwordx4 v[174:177], v[244:245], off offset:3088
	global_load_dwordx4 v[178:181], v[244:245], off offset:3072
	s_branch .Lgu_ld_done
.Lgu_ld_hi:
	global_load_dwordx4 v[196:199], v[246:247], off offset:48
	global_load_dwordx4 v[200:203], v[246:247], off offset:32
	global_load_dwordx4 v[204:207], v[246:247], off offset:16
	global_load_dwordx4 v[208:211], v[246:247], off
	global_load_dwordx4 v[212:215], v[246:247], off offset:1072
	global_load_dwordx4 v[216:219], v[246:247], off offset:1056
	global_load_dwordx4 v[220:223], v[246:247], off offset:1040
	global_load_dwordx4 v[224:227], v[246:247], off offset:1024
	global_load_dwordx4 v[228:231], v[246:247], off offset:2096
	global_load_dwordx4 v[232:235], v[246:247], off offset:2080
	global_load_dwordx4 v[236:239], v[246:247], off offset:2064
	global_load_dwordx4 v[240:243], v[246:247], off offset:2048
	global_load_dwordx4 v[164:167], v[246:247], off offset:3120
	global_load_dwordx4 v[168:171], v[246:247], off offset:3104
	global_load_dwordx4 v[174:177], v[246:247], off offset:3088
	global_load_dwordx4 v[178:181], v[246:247], off offset:3072

.LBB0_1653:
	v_mov_b64_e32 v[248:249], s[50:51]
	s_lshl_b32 s18, s33, 7
	s_ashr_i32 s19, s18, 31
	s_lshl_b64 s[18:19], s[18:19], 1
	v_lshl_add_u64 v[248:249], v[248:249], 0, s[18:19]
	v_lshl_add_u64 v[248:249], v[248:249], 0, s[54:55]
	v_lshl_add_u64 v[248:249], v[248:249], 0, v[0:1]
	s_cmp_eq_u32 s32, 2
	s_cbranch_scc1 .Lgu_epi_hi
	s_waitcnt vmcnt(12)
	v_add_f32_e32 v154, v208, v209
	v_add_f32_e32 v155, v210, v211
	v_add_f32_e32 v154, v154, v155
	v_add_f32_e32 v155, v204, v205
	v_add_f32_e32 v182, v206, v207
	v_add_f32_e32 v155, v155, v182
	v_add_f32_e32 v154, v154, v155
	v_add_f32_e32 v155, v200, v201
	v_add_f32_e32 v182, v202, v203
	v_add_f32_e32 v155, v155, v182
	v_add_f32_e32 v154, v154, v155
	v_add_f32_e32 v155, v196, v197
	v_add_f32_e32 v182, v198, v199
	v_add_f32_e32 v155, v155, v182
	v_add_f32_e32 v154, v154, v155
	v_fmamk_f32 v154, v154, 0x3a800000, v184
	v_rsq_f32_e32 v154, v154
	global_load_dwordx4 v[196:199], v[246:247], off offset:48
	global_load_dwordx4 v[200:203], v[246:247], off offset:32
	global_load_dwordx4 v[204:207], v[246:247], off offset:16
	global_load_dwordx4 v[208:211], v[246:247], off
	v_pk_mul_f32 v[126:127], v[126:127], v[122:123]
	v_pk_mul_f32 v[128:129], v[128:129], v[124:125]
	v_mul_f32_e32 v158, 0xbfb8aa3b, v154
	v_mul_f32_e32 v156, v154, v154
	v_pk_mul_f32 v[118:119], v[118:119], v[114:115]
	v_pk_mul_f32 v[120:121], v[120:121], v[116:117]
	v_pk_mul_f32 v[122:123], v[122:123], v[158:159] op_sel_hi:[1,0]
	v_pk_mul_f32 v[124:125], v[124:125], v[158:159] op_sel_hi:[1,0]
	v_pk_mul_f32 v[114:115], v[114:115], v[158:159] op_sel_hi:[1,0]
	v_pk_mul_f32 v[116:117], v[116:117], v[158:159] op_sel_hi:[1,0]
	v_exp_f32_e32 v122, v122
	v_exp_f32_e32 v123, v123
	v_exp_f32_e32 v124, v124
	v_exp_f32_e32 v125, v125
	v_exp_f32_e32 v114, v114
	v_exp_f32_e32 v115, v115
	v_exp_f32_e32 v116, v116
	v_exp_f32_e32 v117, v117
	v_pk_add_f32 v[122:123], v[122:123], 1.0 op_sel_hi:[1,0]
	v_pk_add_f32 v[124:125], v[124:125], 1.0 op_sel_hi:[1,0]
	v_pk_add_f32 v[114:115], v[114:115], 1.0 op_sel_hi:[1,0]
	v_pk_add_f32 v[116:117], v[116:117], 1.0 op_sel_hi:[1,0]
	v_rcp_f32_e32 v122, v122
	v_rcp_f32_e32 v123, v123
	v_rcp_f32_e32 v124, v124
	v_rcp_f32_e32 v125, v125
	v_rcp_f32_e32 v114, v114
	v_rcp_f32_e32 v115, v115
	v_rcp_f32_e32 v116, v116
	v_rcp_f32_e32 v117, v117
	v_mad_i64_i32 v[250:251], s[0:1], v252, s56, v[248:249]
	v_pk_mul_f32 v[122:123], v[156:157], v[122:123] op_sel_hi:[0,1]
	v_pk_mul_f32 v[124:125], v[156:157], v[124:125] op_sel_hi:[0,1]
	v_pk_mul_f32 v[114:115], v[156:157], v[114:115] op_sel_hi:[0,1]
	v_pk_mul_f32 v[116:117], v[156:157], v[116:117] op_sel_hi:[0,1]
	v_pk_mul_f32 v[126:127], v[126:127], v[122:123]
	v_pk_mul_f32 v[128:129], v[128:129], v[124:125]
	v_pk_mul_f32 v[118:119], v[118:119], v[114:115]
	v_pk_mul_f32 v[120:121], v[120:121], v[116:117]
	v_cvt_pk_bf16_f32 v122, v126, v127
	v_cvt_pk_bf16_f32 v123, v128, v129
	v_cvt_pk_bf16_f32 v124, v118, v119
	v_cvt_pk_bf16_f32 v125, v120, v121
	global_store_dwordx4 v[250:251], v[122:125], off sc1
	s_waitcnt vmcnt(13)
	v_add_f32_e32 v154, v224, v225
	v_add_f32_e32 v155, v226, v227
	v_add_f32_e32 v154, v154, v155
	v_add_f32_e32 v155, v220, v221
	v_add_f32_e32 v182, v222, v223
	v_add_f32_e32 v155, v155, v182
	v_add_f32_e32 v154, v154, v155
	v_add_f32_e32 v155, v216, v217
	v_add_f32_e32 v182, v218, v219
	v_add_f32_e32 v155, v155, v182
	v_add_f32_e32 v154, v154, v155
	v_add_f32_e32 v155, v212, v213
	v_add_f32_e32 v182, v214, v215
	v_add_f32_e32 v155, v155, v182
	v_add_f32_e32 v154, v154, v155
	v_fmamk_f32 v154, v154, 0x3a800000, v184
	v_rsq_f32_e32 v154, v154
	global_load_dwordx4 v[212:215], v[246:247], off offset:1072
	global_load_dwordx4 v[216:219], v[246:247], off offset:1056
	global_load_dwordx4 v[220:223], v[246:247], off offset:1040
	global_load_dwordx4 v[224:227], v[246:247], off offset:1024
	v_pk_mul_f32 v[110:111], v[110:111], v[106:107]
	v_pk_mul_f32 v[112:113], v[112:113], v[108:109]
	v_mul_f32_e32 v158, 0xbfb8aa3b, v154
	v_mul_f32_e32 v156, v154, v154
	v_pk_mul_f32 v[102:103], v[102:103], v[98:99]
	v_pk_mul_f32 v[104:105], v[104:105], v[100:101]
	v_pk_mul_f32 v[106:107], v[106:107], v[158:159] op_sel_hi:[1,0]
	v_pk_mul_f32 v[108:109], v[108:109], v[158:159] op_sel_hi:[1,0]
	v_pk_mul_f32 v[98:99], v[98:99], v[158:159] op_sel_hi:[1,0]
	v_pk_mul_f32 v[100:101], v[100:101], v[158:159] op_sel_hi:[1,0]
	v_exp_f32_e32 v106, v106
	v_exp_f32_e32 v107, v107
	v_exp_f32_e32 v108, v108
	v_exp_f32_e32 v109, v109
	v_exp_f32_e32 v98, v98
	v_exp_f32_e32 v99, v99
	v_exp_f32_e32 v100, v100
	v_exp_f32_e32 v101, v101
	v_pk_add_f32 v[106:107], v[106:107], 1.0 op_sel_hi:[1,0]
	v_pk_add_f32 v[108:109], v[108:109], 1.0 op_sel_hi:[1,0]
	v_pk_add_f32 v[98:99], v[98:99], 1.0 op_sel_hi:[1,0]
	v_pk_add_f32 v[100:101], v[100:101], 1.0 op_sel_hi:[1,0]
	v_rcp_f32_e32 v106, v106
	v_rcp_f32_e32 v107, v107
	v_rcp_f32_e32 v108, v108
	v_rcp_f32_e32 v109, v109
	v_rcp_f32_e32 v98, v98
	v_rcp_f32_e32 v99, v99
	v_rcp_f32_e32 v100, v100
	v_rcp_f32_e32 v101, v101
	v_add_u32_e32 v250, 16, v252
	v_mad_i64_i32 v[250:251], s[0:1], v250, s56, v[248:249]
	v_pk_mul_f32 v[106:107], v[156:157], v[106:107] op_sel_hi:[0,1]
	v_pk_mul_f32 v[108:109], v[156:157], v[108:109] op_sel_hi:[0,1]
	v_pk_mul_f32 v[98:99], v[156:157], v[98:99] op_sel_hi:[0,1]
	v_pk_mul_f32 v[100:101], v[156:157], v[100:101] op_sel_hi:[0,1]
	v_pk_mul_f32 v[110:111], v[110:111], v[106:107]
	v_pk_mul_f32 v[112:113], v[112:113], v[108:109]
	v_pk_mul_f32 v[102:103], v[102:103], v[98:99]
	v_pk_mul_f32 v[104:105], v[104:105], v[100:101]
	v_cvt_pk_bf16_f32 v106, v110, v111
	v_cvt_pk_bf16_f32 v107, v112, v113
	v_cvt_pk_bf16_f32 v108, v102, v103
	v_cvt_pk_bf16_f32 v109, v104, v105
	global_store_dwordx4 v[250:251], v[106:109], off sc1
	s_waitcnt vmcnt(14)
	v_add_f32_e32 v154, v240, v241
	v_add_f32_e32 v155, v242, v243
	v_add_f32_e32 v154, v154, v155
	v_add_f32_e32 v155, v236, v237
	v_add_f32_e32 v182, v238, v239
	v_add_f32_e32 v155, v155, v182
	v_add_f32_e32 v154, v154, v155
	v_add_f32_e32 v155, v232, v233
	v_add_f32_e32 v182, v234, v235
	v_add_f32_e32 v155, v155, v182
	v_add_f32_e32 v154, v154, v155
	v_add_f32_e32 v155, v228, v229
	v_add_f32_e32 v182, v230, v231
	v_add_f32_e32 v155, v155, v182
	v_add_f32_e32 v154, v154, v155
	v_fmamk_f32 v154, v154, 0x3a800000, v184
	v_rsq_f32_e32 v154, v154
	global_load_dwordx4 v[228:231], v[246:247], off offset:2096
	global_load_dwordx4 v[232:235], v[246:247], off offset:2080
	global_load_dwordx4 v[236:239], v[246:247], off offset:2064
	global_load_dwordx4 v[240:243], v[246:247], off offset:2048
	v_pk_mul_f32 v[94:95], v[94:95], v[90:91]
	v_pk_mul_f32 v[96:97], v[96:97], v[92:93]
	v_mul_f32_e32 v158, 0xbfb8aa3b, v154
	v_mul_f32_e32 v156, v154, v154
	v_pk_mul_f32 v[86:87], v[86:87], v[82:83]
	v_pk_mul_f32 v[88:89], v[88:89], v[84:85]
	v_pk_mul_f32 v[90:91], v[90:91], v[158:159] op_sel_hi:[1,0]
	v_pk_mul_f32 v[92:93], v[92:93], v[158:159] op_sel_hi:[1,0]
	v_pk_mul_f32 v[82:83], v[82:83], v[158:159] op_sel_hi:[1,0]
	v_pk_mul_f32 v[84:85], v[84:85], v[158:159] op_sel_hi:[1,0]
	v_exp_f32_e32 v90, v90
	v_exp_f32_e32 v91, v91
	v_exp_f32_e32 v92, v92
	v_exp_f32_e32 v93, v93
	v_exp_f32_e32 v82, v82
	v_exp_f32_e32 v83, v83
	v_exp_f32_e32 v84, v84
	v_exp_f32_e32 v85, v85
	v_pk_add_f32 v[90:91], v[90:91], 1.0 op_sel_hi:[1,0]
	v_pk_add_f32 v[92:93], v[92:93], 1.0 op_sel_hi:[1,0]
	v_pk_add_f32 v[82:83], v[82:83], 1.0 op_sel_hi:[1,0]
	v_pk_add_f32 v[84:85], v[84:85], 1.0 op_sel_hi:[1,0]
	v_rcp_f32_e32 v90, v90
	v_rcp_f32_e32 v91, v91
	v_rcp_f32_e32 v92, v92
	v_rcp_f32_e32 v93, v93
	v_rcp_f32_e32 v82, v82
	v_rcp_f32_e32 v83, v83
	v_rcp_f32_e32 v84, v84
	v_rcp_f32_e32 v85, v85
	v_add_u32_e32 v250, 32, v252
	v_mad_i64_i32 v[250:251], s[0:1], v250, s56, v[248:249]
	v_pk_mul_f32 v[90:91], v[156:157], v[90:91] op_sel_hi:[0,1]
	v_pk_mul_f32 v[92:93], v[156:157], v[92:93] op_sel_hi:[0,1]
	v_pk_mul_f32 v[82:83], v[156:157], v[82:83] op_sel_hi:[0,1]
	v_pk_mul_f32 v[84:85], v[156:157], v[84:85] op_sel_hi:[0,1]
	v_pk_mul_f32 v[94:95], v[94:95], v[90:91]
	v_pk_mul_f32 v[96:97], v[96:97], v[92:93]
	v_pk_mul_f32 v[86:87], v[86:87], v[82:83]
	v_pk_mul_f32 v[88:89], v[88:89], v[84:85]
	v_cvt_pk_bf16_f32 v90, v94, v95
	v_cvt_pk_bf16_f32 v91, v96, v97
	v_cvt_pk_bf16_f32 v92, v86, v87
	v_cvt_pk_bf16_f32 v93, v88, v89
	global_store_dwordx4 v[250:251], v[90:93], off sc1
	s_waitcnt vmcnt(15)
	v_add_f32_e32 v154, v178, v179
	v_add_f32_e32 v155, v180, v181
	v_add_f32_e32 v154, v154, v155
	v_add_f32_e32 v155, v174, v175
	v_add_f32_e32 v182, v176, v177
	v_add_f32_e32 v155, v155, v182
	v_add_f32_e32 v154, v154, v155
	v_add_f32_e32 v155, v168, v169
	v_add_f32_e32 v182, v170, v171
	v_add_f32_e32 v155, v155, v182
	v_add_f32_e32 v154, v154, v155
	v_add_f32_e32 v155, v164, v165
	v_add_f32_e32 v182, v166, v167
	v_add_f32_e32 v155, v155, v182
	v_add_f32_e32 v154, v154, v155
	v_fmamk_f32 v154, v154, 0x3a800000, v184
	v_rsq_f32_e32 v154, v154
	global_load_dwordx4 v[164:167], v[246:247], off offset:3120
	global_load_dwordx4 v[168:171], v[246:247], off offset:3104
	global_load_dwordx4 v[174:177], v[246:247], off offset:3088
	global_load_dwordx4 v[178:181], v[246:247], off offset:3072
	v_pk_mul_f32 v[78:79], v[78:79], v[74:75]
	v_pk_mul_f32 v[80:81], v[80:81], v[76:77]
	v_mul_f32_e32 v158, 0xbfb8aa3b, v154
	v_mul_f32_e32 v156, v154, v154
	v_pk_mul_f32 v[70:71], v[70:71], v[66:67]
	v_pk_mul_f32 v[72:73], v[72:73], v[68:69]
	v_pk_mul_f32 v[74:75], v[74:75], v[158:159] op_sel_hi:[1,0]
	v_pk_mul_f32 v[76:77], v[76:77], v[158:159] op_sel_hi:[1,0]
	v_pk_mul_f32 v[66:67], v[66:67], v[158:159] op_sel_hi:[1,0]
	v_pk_mul_f32 v[68:69], v[68:69], v[158:159] op_sel_hi:[1,0]
	v_exp_f32_e32 v74, v74
	v_exp_f32_e32 v75, v75
	v_exp_f32_e32 v76, v76
	v_exp_f32_e32 v77, v77
	v_exp_f32_e32 v66, v66
	v_exp_f32_e32 v67, v67
	v_exp_f32_e32 v68, v68
	v_exp_f32_e32 v69, v69
	v_pk_add_f32 v[74:75], v[74:75], 1.0 op_sel_hi:[1,0]
	v_pk_add_f32 v[76:77], v[76:77], 1.0 op_sel_hi:[1,0]
	v_pk_add_f32 v[66:67], v[66:67], 1.0 op_sel_hi:[1,0]
	v_pk_add_f32 v[68:69], v[68:69], 1.0 op_sel_hi:[1,0]
	v_rcp_f32_e32 v74, v74
	v_rcp_f32_e32 v75, v75
	v_rcp_f32_e32 v76, v76
	v_rcp_f32_e32 v77, v77
	v_rcp_f32_e32 v66, v66
	v_rcp_f32_e32 v67, v67
	v_rcp_f32_e32 v68, v68
	v_rcp_f32_e32 v69, v69
	v_add_u32_e32 v250, 48, v252
	v_mad_i64_i32 v[250:251], s[0:1], v250, s56, v[248:249]
	v_pk_mul_f32 v[74:75], v[156:157], v[74:75] op_sel_hi:[0,1]
	v_pk_mul_f32 v[76:77], v[156:157], v[76:77] op_sel_hi:[0,1]
	v_pk_mul_f32 v[66:67], v[156:157], v[66:67] op_sel_hi:[0,1]
	v_pk_mul_f32 v[68:69], v[156:157], v[68:69] op_sel_hi:[0,1]
	v_pk_mul_f32 v[78:79], v[78:79], v[74:75]
	v_pk_mul_f32 v[80:81], v[80:81], v[76:77]
	v_pk_mul_f32 v[70:71], v[70:71], v[66:67]
	v_pk_mul_f32 v[72:73], v[72:73], v[68:69]
	v_cvt_pk_bf16_f32 v74, v78, v79
	v_cvt_pk_bf16_f32 v75, v80, v81
	v_cvt_pk_bf16_f32 v76, v70, v71
	v_cvt_pk_bf16_f32 v77, v72, v73
	global_store_dwordx4 v[250:251], v[74:77], off sc1
	s_cmp_eq_u32 s32, 1
	s_cbranch_scc0 .Lgu_epi_hi
	s_waitcnt vmcnt(0)
	s_branch .Lgu_epi_end
.Lgu_epi_hi:
	s_waitcnt vmcnt(12)
	v_add_f32_e32 v154, v208, v209
	v_add_f32_e32 v155, v210, v211
	v_add_f32_e32 v154, v154, v155
	v_add_f32_e32 v155, v204, v205
	v_add_f32_e32 v182, v206, v207
	v_add_f32_e32 v155, v155, v182
	v_add_f32_e32 v154, v154, v155
	v_add_f32_e32 v155, v200, v201
	v_add_f32_e32 v182, v202, v203
	v_add_f32_e32 v155, v155, v182
	v_add_f32_e32 v154, v154, v155
	v_add_f32_e32 v155, v196, v197
	v_add_f32_e32 v182, v198, v199
	v_add_f32_e32 v155, v155, v182
	v_add_f32_e32 v154, v154, v155
	v_fmamk_f32 v154, v154, 0x3a800000, v184
	v_rsq_f32_e32 v154, v154
	v_pk_mul_f32 v[62:63], v[62:63], v[58:59]
	v_pk_mul_f32 v[64:65], v[64:65], v[60:61]
	v_mul_f32_e32 v158, 0xbfb8aa3b, v154
	v_mul_f32_e32 v156, v154, v154
	v_pk_mul_f32 v[54:55], v[54:55], v[50:51]
	v_pk_mul_f32 v[56:57], v[56:57], v[52:53]
	v_pk_mul_f32 v[58:59], v[58:59], v[158:159] op_sel_hi:[1,0]
	v_pk_mul_f32 v[60:61], v[60:61], v[158:159] op_sel_hi:[1,0]
	v_pk_mul_f32 v[50:51], v[50:51], v[158:159] op_sel_hi:[1,0]
	v_pk_mul_f32 v[52:53], v[52:53], v[158:159] op_sel_hi:[1,0]
	v_exp_f32_e32 v58, v58
	v_exp_f32_e32 v59, v59
	v_exp_f32_e32 v60, v60
	v_exp_f32_e32 v61, v61
	v_exp_f32_e32 v50, v50
	v_exp_f32_e32 v51, v51
	v_exp_f32_e32 v52, v52
	v_exp_f32_e32 v53, v53
	v_pk_add_f32 v[58:59], v[58:59], 1.0 op_sel_hi:[1,0]
	v_pk_add_f32 v[60:61], v[60:61], 1.0 op_sel_hi:[1,0]
	v_pk_add_f32 v[50:51], v[50:51], 1.0 op_sel_hi:[1,0]
	v_pk_add_f32 v[52:53], v[52:53], 1.0 op_sel_hi:[1,0]
	v_rcp_f32_e32 v58, v58
	v_rcp_f32_e32 v59, v59
	v_rcp_f32_e32 v60, v60
	v_rcp_f32_e32 v61, v61
	v_rcp_f32_e32 v50, v50
	v_rcp_f32_e32 v51, v51
	v_rcp_f32_e32 v52, v52
	v_rcp_f32_e32 v53, v53
	v_add_u32_e32 v250, 128, v252
	v_mad_i64_i32 v[250:251], s[0:1], v250, s56, v[248:249]
	v_pk_mul_f32 v[58:59], v[156:157], v[58:59] op_sel_hi:[0,1]
	v_pk_mul_f32 v[60:61], v[156:157], v[60:61] op_sel_hi:[0,1]
	v_pk_mul_f32 v[50:51], v[156:157], v[50:51] op_sel_hi:[0,1]
	v_pk_mul_f32 v[52:53], v[156:157], v[52:53] op_sel_hi:[0,1]
	v_pk_mul_f32 v[62:63], v[62:63], v[58:59]
	v_pk_mul_f32 v[64:65], v[64:65], v[60:61]
	v_pk_mul_f32 v[54:55], v[54:55], v[50:51]
	v_pk_mul_f32 v[56:57], v[56:57], v[52:53]
	v_cvt_pk_bf16_f32 v58, v62, v63
	v_cvt_pk_bf16_f32 v59, v64, v65
	v_cvt_pk_bf16_f32 v60, v54, v55
	v_cvt_pk_bf16_f32 v61, v56, v57
	global_store_dwordx4 v[250:251], v[58:61], off sc1
	s_waitcnt vmcnt(9)
	v_add_f32_e32 v154, v224, v225
	v_add_f32_e32 v155, v226, v227
	v_add_f32_e32 v154, v154, v155
	v_add_f32_e32 v155, v220, v221
	v_add_f32_e32 v182, v222, v223
	v_add_f32_e32 v155, v155, v182
	v_add_f32_e32 v154, v154, v155
	v_add_f32_e32 v155, v216, v217
	v_add_f32_e32 v182, v218, v219
	v_add_f32_e32 v155, v155, v182
	v_add_f32_e32 v154, v154, v155
	v_add_f32_e32 v155, v212, v213
	v_add_f32_e32 v182, v214, v215
	v_add_f32_e32 v155, v155, v182
	v_add_f32_e32 v154, v154, v155
	v_fmamk_f32 v154, v154, 0x3a800000, v184
	v_rsq_f32_e32 v154, v154
	v_pk_mul_f32 v[46:47], v[46:47], v[42:43]
	v_pk_mul_f32 v[48:49], v[48:49], v[44:45]
	v_mul_f32_e32 v158, 0xbfb8aa3b, v154
	v_mul_f32_e32 v156, v154, v154
	v_pk_mul_f32 v[38:39], v[38:39], v[34:35]
	v_pk_mul_f32 v[40:41], v[40:41], v[36:37]
	v_pk_mul_f32 v[42:43], v[42:43], v[158:159] op_sel_hi:[1,0]
	v_pk_mul_f32 v[44:45], v[44:45], v[158:159] op_sel_hi:[1,0]
	v_pk_mul_f32 v[34:35], v[34:35], v[158:159] op_sel_hi:[1,0]
	v_pk_mul_f32 v[36:37], v[36:37], v[158:159] op_sel_hi:[1,0]
	v_exp_f32_e32 v42, v42
	v_exp_f32_e32 v43, v43
	v_exp_f32_e32 v44, v44
	v_exp_f32_e32 v45, v45
	v_exp_f32_e32 v34, v34
	v_exp_f32_e32 v35, v35
	v_exp_f32_e32 v36, v36
	v_exp_f32_e32 v37, v37
	v_pk_add_f32 v[42:43], v[42:43], 1.0 op_sel_hi:[1,0]
	v_pk_add_f32 v[44:45], v[44:45], 1.0 op_sel_hi:[1,0]
	v_pk_add_f32 v[34:35], v[34:35], 1.0 op_sel_hi:[1,0]
	v_pk_add_f32 v[36:37], v[36:37], 1.0 op_sel_hi:[1,0]
	v_rcp_f32_e32 v42, v42
	v_rcp_f32_e32 v43, v43
	v_rcp_f32_e32 v44, v44
	v_rcp_f32_e32 v45, v45
	v_rcp_f32_e32 v34, v34
	v_rcp_f32_e32 v35, v35
	v_rcp_f32_e32 v36, v36
	v_rcp_f32_e32 v37, v37
	v_add_u32_e32 v250, 144, v252
	v_mad_i64_i32 v[250:251], s[0:1], v250, s56, v[248:249]
	v_pk_mul_f32 v[42:43], v[156:157], v[42:43] op_sel_hi:[0,1]
	v_pk_mul_f32 v[44:45], v[156:157], v[44:45] op_sel_hi:[0,1]
	v_pk_mul_f32 v[34:35], v[156:157], v[34:35] op_sel_hi:[0,1]
	v_pk_mul_f32 v[36:37], v[156:157], v[36:37] op_sel_hi:[0,1]
	v_pk_mul_f32 v[46:47], v[46:47], v[42:43]
	v_pk_mul_f32 v[48:49], v[48:49], v[44:45]
	v_pk_mul_f32 v[38:39], v[38:39], v[34:35]
	v_pk_mul_f32 v[40:41], v[40:41], v[36:37]
	v_cvt_pk_bf16_f32 v42, v46, v47
	v_cvt_pk_bf16_f32 v43, v48, v49
	v_cvt_pk_bf16_f32 v44, v38, v39
	v_cvt_pk_bf16_f32 v45, v40, v41
	global_store_dwordx4 v[250:251], v[42:45], off sc1
	s_waitcnt vmcnt(6)
	v_add_f32_e32 v154, v240, v241
	v_add_f32_e32 v155, v242, v243
	v_add_f32_e32 v154, v154, v155
	v_add_f32_e32 v155, v236, v237
	v_add_f32_e32 v182, v238, v239
	v_add_f32_e32 v155, v155, v182
	v_add_f32_e32 v154, v154, v155
	v_add_f32_e32 v155, v232, v233
	v_add_f32_e32 v182, v234, v235
	v_add_f32_e32 v155, v155, v182
	v_add_f32_e32 v154, v154, v155
	v_add_f32_e32 v155, v228, v229
	v_add_f32_e32 v182, v230, v231
	v_add_f32_e32 v155, v155, v182
	v_add_f32_e32 v154, v154, v155
	v_fmamk_f32 v154, v154, 0x3a800000, v184
	v_rsq_f32_e32 v154, v154
	v_pk_mul_f32 v[30:31], v[30:31], v[26:27]
	v_pk_mul_f32 v[32:33], v[32:33], v[28:29]
	v_mul_f32_e32 v158, 0xbfb8aa3b, v154
	v_mul_f32_e32 v156, v154, v154
	v_pk_mul_f32 v[22:23], v[22:23], v[18:19]
	v_pk_mul_f32 v[24:25], v[24:25], v[20:21]
	v_pk_mul_f32 v[26:27], v[26:27], v[158:159] op_sel_hi:[1,0]
	v_pk_mul_f32 v[28:29], v[28:29], v[158:159] op_sel_hi:[1,0]
	v_pk_mul_f32 v[18:19], v[18:19], v[158:159] op_sel_hi:[1,0]
	v_pk_mul_f32 v[20:21], v[20:21], v[158:159] op_sel_hi:[1,0]
	v_exp_f32_e32 v26, v26
	v_exp_f32_e32 v27, v27
	v_exp_f32_e32 v28, v28
	v_exp_f32_e32 v29, v29
	v_exp_f32_e32 v18, v18
	v_exp_f32_e32 v19, v19
	v_exp_f32_e32 v20, v20
	v_exp_f32_e32 v21, v21
	v_pk_add_f32 v[26:27], v[26:27], 1.0 op_sel_hi:[1,0]
	v_pk_add_f32 v[28:29], v[28:29], 1.0 op_sel_hi:[1,0]
	v_pk_add_f32 v[18:19], v[18:19], 1.0 op_sel_hi:[1,0]
	v_pk_add_f32 v[20:21], v[20:21], 1.0 op_sel_hi:[1,0]
	v_rcp_f32_e32 v26, v26
	v_rcp_f32_e32 v27, v27
	v_rcp_f32_e32 v28, v28
	v_rcp_f32_e32 v29, v29
	v_rcp_f32_e32 v18, v18
	v_rcp_f32_e32 v19, v19
	v_rcp_f32_e32 v20, v20
	v_rcp_f32_e32 v21, v21
	v_add_u32_e32 v250, 160, v252
	v_mad_i64_i32 v[250:251], s[0:1], v250, s56, v[248:249]
	v_pk_mul_f32 v[26:27], v[156:157], v[26:27] op_sel_hi:[0,1]
	v_pk_mul_f32 v[28:29], v[156:157], v[28:29] op_sel_hi:[0,1]
	v_pk_mul_f32 v[18:19], v[156:157], v[18:19] op_sel_hi:[0,1]
	v_pk_mul_f32 v[20:21], v[156:157], v[20:21] op_sel_hi:[0,1]
	v_pk_mul_f32 v[30:31], v[30:31], v[26:27]
	v_pk_mul_f32 v[32:33], v[32:33], v[28:29]
	v_pk_mul_f32 v[22:23], v[22:23], v[18:19]
	v_pk_mul_f32 v[24:25], v[24:25], v[20:21]
	v_cvt_pk_bf16_f32 v26, v30, v31
	v_cvt_pk_bf16_f32 v27, v32, v33
	v_cvt_pk_bf16_f32 v28, v22, v23
	v_cvt_pk_bf16_f32 v29, v24, v25
	global_store_dwordx4 v[250:251], v[26:29], off sc1
	s_waitcnt vmcnt(3)
	v_add_f32_e32 v154, v178, v179
	v_add_f32_e32 v155, v180, v181
	v_add_f32_e32 v154, v154, v155
	v_add_f32_e32 v155, v174, v175
	v_add_f32_e32 v182, v176, v177
	v_add_f32_e32 v155, v155, v182
	v_add_f32_e32 v154, v154, v155
	v_add_f32_e32 v155, v168, v169
	v_add_f32_e32 v182, v170, v171
	v_add_f32_e32 v155, v155, v182
	v_add_f32_e32 v154, v154, v155
	v_add_f32_e32 v155, v164, v165
	v_add_f32_e32 v182, v166, v167
	v_add_f32_e32 v155, v155, v182
	v_add_f32_e32 v154, v154, v155
	v_fmamk_f32 v154, v154, 0x3a800000, v184
	v_rsq_f32_e32 v154, v154
	v_pk_mul_f32 v[14:15], v[14:15], v[10:11]
	v_pk_mul_f32 v[16:17], v[16:17], v[12:13]
	v_mul_f32_e32 v158, 0xbfb8aa3b, v154
	v_mul_f32_e32 v156, v154, v154
	v_pk_mul_f32 v[2:3], v[2:3], v[6:7]
	v_pk_mul_f32 v[4:5], v[4:5], v[8:9]
	v_pk_mul_f32 v[10:11], v[10:11], v[158:159] op_sel_hi:[1,0]
	v_pk_mul_f32 v[12:13], v[12:13], v[158:159] op_sel_hi:[1,0]
	v_pk_mul_f32 v[6:7], v[6:7], v[158:159] op_sel_hi:[1,0]
	v_pk_mul_f32 v[8:9], v[8:9], v[158:159] op_sel_hi:[1,0]
	v_exp_f32_e32 v10, v10
	v_exp_f32_e32 v11, v11
	v_exp_f32_e32 v12, v12
	v_exp_f32_e32 v13, v13
	v_exp_f32_e32 v6, v6
	v_exp_f32_e32 v7, v7
	v_exp_f32_e32 v8, v8
	v_exp_f32_e32 v9, v9
	v_pk_add_f32 v[10:11], v[10:11], 1.0 op_sel_hi:[1,0]
	v_pk_add_f32 v[12:13], v[12:13], 1.0 op_sel_hi:[1,0]
	v_pk_add_f32 v[6:7], v[6:7], 1.0 op_sel_hi:[1,0]
	v_pk_add_f32 v[8:9], v[8:9], 1.0 op_sel_hi:[1,0]
	v_rcp_f32_e32 v10, v10
	v_rcp_f32_e32 v11, v11
	v_rcp_f32_e32 v12, v12
	v_rcp_f32_e32 v13, v13
	v_rcp_f32_e32 v6, v6
	v_rcp_f32_e32 v7, v7
	v_rcp_f32_e32 v8, v8
	v_rcp_f32_e32 v9, v9
	v_add_u32_e32 v250, 176, v252
	v_mad_i64_i32 v[250:251], s[0:1], v250, s56, v[248:249]
	v_pk_mul_f32 v[10:11], v[156:157], v[10:11] op_sel_hi:[0,1]
	v_pk_mul_f32 v[12:13], v[156:157], v[12:13] op_sel_hi:[0,1]
	v_pk_mul_f32 v[6:7], v[156:157], v[6:7] op_sel_hi:[0,1]
	v_pk_mul_f32 v[8:9], v[156:157], v[8:9] op_sel_hi:[0,1]
	v_pk_mul_f32 v[14:15], v[14:15], v[10:11]
	v_pk_mul_f32 v[16:17], v[16:17], v[12:13]
	v_pk_mul_f32 v[2:3], v[2:3], v[6:7]
	v_pk_mul_f32 v[4:5], v[4:5], v[8:9]
	v_cvt_pk_bf16_f32 v10, v14, v15
	v_cvt_pk_bf16_f32 v11, v16, v17
	v_cvt_pk_bf16_f32 v12, v2, v3
	v_cvt_pk_bf16_f32 v13, v4, v5
	global_store_dwordx4 v[250:251], v[10:13], off sc1
.Lgu_epi_end:
	s_and_b64 vcc, exec, s[2:3]
	s_mov_b64 s[0:1], -1
	s_cbranch_vccnz .LBB0_1641
	s_andn2_b64 vcc, exec, s[10:11]
	s_cbranch_vccnz .LBB0_1640
	s_barrier
	s_branch .LBB0_1640
